# strip output: v_permlane32_swap pairs + 4 dwordx4 stores instead of 8 row-per-lane dwordx2
# speedup vs baseline: 1.0009x; 1.0009x over previous
; __device__ __forceinline__ unsigned cvtpk_s(float lo, float hi) { f32x2_t v = {lo, hi}; bf16x2_t b = __builtin_convertvector(v, bf16x2_t); return __builtin_bit_cast(unsigned, b); }
; __device__ __forceinline__ void sb_strip(const bf16* SQ, const bf16* SK, const bf16* SV, bf16* OMIX, int h, int qpos0, int lane, LAS unsigned char* vl) {
;     ...
;     bf16* op = OMIX + (size_t)qrow * 1024 + 512 + h * 64 + 4 * hi;
; #pragma unroll
;     for (int g = 0; g < 4; ++g) {
;         unsigned long long a = (unsigned long long)cvtpk_s(o0[4 * g], o0[4 * g + 1]) | ((unsigned long long)cvtpk_s(o0[4 * g + 2], o0[4 * g + 3]) << 32);
;         unsigned long long b = (unsigned long long)cvtpk_s(o1[4 * g], o1[4 * g + 1]) | ((unsigned long long)cvtpk_s(o1[4 * g + 2], o1[4 * g + 3]) << 32);
;         *(unsigned long long*)(op + 8 * g) = a; *(unsigned long long*)(op + 32 + 8 * g) = b; }
.LBB0_1042:
	v_readlane_b32 s48, v237, 7
	v_lshlrev_b32_e32 v0, 11, v192
	v_readlane_b32 s62, v237, 21
	v_readlane_b32 s63, v237, 22
	v_lshl_add_u64 v[34:35], s[62:63], 0, v[0:1]
	v_lshl_add_u64 v[34:35], s[24:25], 1, v[34:35]
	v_lshlrev_b32_e32 v0, 2, v180
	v_lshl_add_u64 v[34:35], v[34:35], 0, v[0:1]
	v_cvt_pk_bf16_f32 v36, v2, v3
	v_cvt_pk_bf16_f32 v37, v4, v5
	v_cvt_pk_bf16_f32 v38, v6, v7
	v_cvt_pk_bf16_f32 v39, v8, v9
	v_cvt_pk_bf16_f32 v40, v10, v11
	v_cvt_pk_bf16_f32 v41, v12, v13
	v_cvt_pk_bf16_f32 v42, v14, v15
	v_cvt_pk_bf16_f32 v43, v16, v17
	v_cvt_pk_bf16_f32 v44, v18, v19
	v_cvt_pk_bf16_f32 v45, v20, v21
	v_cvt_pk_bf16_f32 v46, v22, v23
	v_cvt_pk_bf16_f32 v47, v24, v25
	v_cvt_pk_bf16_f32 v48, v26, v27
	v_cvt_pk_bf16_f32 v49, v28, v29
	v_cvt_pk_bf16_f32 v50, v30, v31
	v_cvt_pk_bf16_f32 v51, v32, v33
	s_add_i32 s28, s28, s29
	s_add_i32 s30, s30, s31
	s_nop 1
	v_permlane32_swap_b32 v36, v38
	v_permlane32_swap_b32 v37, v39
	v_permlane32_swap_b32 v40, v42
	v_permlane32_swap_b32 v41, v43
	v_permlane32_swap_b32 v44, v46
	v_permlane32_swap_b32 v45, v47
	v_permlane32_swap_b32 v48, v50
	v_permlane32_swap_b32 v49, v51
	global_store_dwordx4 v[34:35], v[36:39], off offset:1024
	global_store_dwordx4 v[34:35], v[40:43], off offset:1056
	global_store_dwordx4 v[34:35], v[44:47], off offset:1088
	global_store_dwordx4 v[34:35], v[48:51], off offset:1120
	s_cmpk_lt_i32 s28, 0x1000
	v_readlane_b32 s49, v237, 8
	v_readlane_b32 s50, v237, 9
	v_readlane_b32 s51, v237, 10
	v_readlane_b32 s52, v237, 11
	v_readlane_b32 s53, v237, 12
	v_readlane_b32 s54, v237, 13
	v_readlane_b32 s55, v237, 14
	v_readlane_b32 s56, v237, 15
	v_readlane_b32 s57, v237, 16
	v_readlane_b32 s58, v237, 17
	v_readlane_b32 s59, v237, 18
	v_readlane_b32 s60, v237, 19
	v_readlane_b32 s61, v237, 20
	s_cbranch_scc0 .LBB0_1062
